# static priority raise for waves 0-3 over the whole kernel (no GEMM toggling)
# baseline (speedup 1.0000x reference)
; __device__ __forceinline__ int opaque_tid() { int t = threadIdx.x; asm volatile("" : "+v"(t)); return t; }
; DI PrmC get_prm() { auto k = __builtin_amdgcn_kernarg_segment_ptr(); asm volatile("" : "+s"(k)); return (PrmC)k; }
; #define LAS __attribute__((address_space(3)))
; __device__ __forceinline__ unsigned xb_add(unsigned* p, unsigned v) { return __hip_atomic_fetch_add(p, v, __ATOMIC_RELAXED, __HIP_MEMORY_SCOPE_AGENT); }
; __device__ __forceinline__ unsigned xb_xcc_id() { return (unsigned)__builtin_amdgcn_s_getreg((3 << 11) | 20) & 0xFu; }
; __device__ __forceinline__ XcdBarrier xcd_barrier_post(unsigned* bar, volatile LAS unsigned* st) {
;     XcdBarrier b; b.bar = bar; b.x = xb_xcc_id(); b.st = st;
;     if (threadIdx.x == 0) (void)xb_add(&bar[XB_XCNT(b.x)], 1u);
;     return b;
; __global__ void __launch_bounds__(NTHR, 2) fwd_megakernel(Prm p_unused, int lo, int hi) {
;     extern __shared__ __attribute__((aligned(16))) unsigned char smem[];
;     cg::grid_group grid = cg::this_grid();
;     { const int t0 = opaque_tid(); if (t0 < 4) ((volatile LAS unsigned*)(LAS unsigned char*)(smem + LDS_BYTES - 16))[t0] = 0u; }
;     __syncthreads();
;     if (hi - lo > 1) { PrmC p0 = get_prm(); (void)xcd_barrier_post((unsigned*)(p0->ws + OFF_BAR), (volatile LAS unsigned*)(LAS unsigned char*)(smem + LDS_BYTES - 16)); }
_Z14fwd_megakernel3Prmii:
	s_load_dwordx2 s[90:91], s[0:1], 0xc0
	v_writelane_b32 v254, s2, 0
	s_add_u32 s2, s0, 0xc0
	s_addc_u32 s3, s1, 0
	v_writelane_b32 v254, s2, 1
	v_and_b32_e32 v195, 0x3ff, v0
	v_mov_b32_e32 v1, v195
	v_readfirstlane_b32 s98, v195
	s_cmp_lt_u32 s98, 0x100
	s_cbranch_scc0 .Lprio_all
	s_setprio 1
.Lprio_all:
	v_writelane_b32 v254, s3, 2
	v_writelane_b32 v254, s0, 3
	s_load_dword s2, s[0:1], 0xc8
	s_nop 0
	v_writelane_b32 v254, s1, 4
	v_cmp_gt_i32_e32 vcc, 4, v1
	s_and_saveexec_b64 s[0:1], vcc
	v_lshl_add_u32 v1, v1, 2, 0
	v_add_u32_e32 v1, 0x25ff0, v1
	v_mov_b32_e32 v2, 0
	ds_write_b32 v1, v2
	s_or_b64 exec, exec, s[0:1]
	v_readlane_b32 s0, v254, 3
	v_readlane_b32 s1, v254, 4
	s_load_dwordx2 s[40:41], s[0:1], 0xb8
	v_cmp_eq_u32_e32 vcc, 0, v195
	s_waitcnt lgkmcnt(0)
	s_barrier
	s_sub_i32 s0, s41, s40
	s_cmp_lt_i32 s0, 2
	s_cbranch_scc1 .LBB0_7
	v_readlane_b32 s4, v254, 3
	v_readlane_b32 s5, v254, 4
	s_getreg_b32 s3, hwreg(HW_REG_XCC_ID, 0, 4)
	s_and_saveexec_b64 s[0:1], vcc
	s_cbranch_execz .LBB0_6
	s_mov_b64 s[6:7], exec
	v_mbcnt_lo_u32_b32 v1, s6, 0
	v_mbcnt_hi_u32_b32 v1, s7, v1
	v_cmp_eq_u32_e32 vcc, 0, v1
	s_and_b64 s[8:9], exec, vcc
	s_mov_b64 exec, s[8:9]
	s_cbranch_execz .LBB0_6
	s_load_dwordx2 s[4:5], s[4:5], 0xb0
	s_lshl_b32 s3, s3, 8
	s_and_b32 s3, s3, 0xf00
	s_bcnt1_i32_b64 s6, s[6:7]
	v_mov_b32_e32 v1, s3
	v_mov_b32_e32 v2, s6
	s_waitcnt lgkmcnt(0)
	global_atomic_add v1, v2, s[4:5] offset:1024
